# control: all non-supertile optimizations, gu in original 128x128 form
# baseline (speedup 1.0000x reference)
; __global__ void __launch_bounds__(NTHR, 2) fwd_megakernel(Params p0) {
;   __shared__ __attribute__((aligned(16))) char lds[65536];
;   cg::grid_group grid = cg::this_grid();
;   __shared__ uint4 xb_words;
	.amdhsa_kernel _Z14fwd_megakernel6Params
		.amdhsa_group_segment_fixed_size 65552
		.amdhsa_private_segment_fixed_size 0
		.amdhsa_kernarg_size 512
		.amdhsa_user_sgpr_count 2
		.amdhsa_user_sgpr_dispatch_ptr 0
		.amdhsa_user_sgpr_queue_ptr 0
		.amdhsa_user_sgpr_kernarg_segment_ptr 1
		.amdhsa_user_sgpr_dispatch_id 0
		.amdhsa_user_sgpr_kernarg_preload_length 0
		.amdhsa_user_sgpr_kernarg_preload_offset 0
		.amdhsa_user_sgpr_private_segment_size 0
		.amdhsa_uses_dynamic_stack 0
		.amdhsa_enable_private_segment 0
		.amdhsa_system_sgpr_workgroup_id_x 1
		.amdhsa_system_sgpr_workgroup_id_y 0
		.amdhsa_system_sgpr_workgroup_id_z 0
		.amdhsa_system_sgpr_workgroup_info 0
		.amdhsa_system_vgpr_workitem_id 2
		.amdhsa_next_free_vgpr 256
		.amdhsa_next_free_sgpr 100
		.amdhsa_accum_offset 256
		.amdhsa_reserve_vcc 1
		.amdhsa_float_round_mode_32 0
		.amdhsa_float_round_mode_16_64 0
		.amdhsa_float_denorm_mode_32 3
		.amdhsa_float_denorm_mode_16_64 3
		.amdhsa_dx10_clamp 1
		.amdhsa_ieee_mode 1
		.amdhsa_fp16_overflow 0
		.amdhsa_tg_split 0
		.amdhsa_exception_fp_ieee_invalid_op 0
		.amdhsa_exception_fp_denorm_src 0
		.amdhsa_exception_fp_ieee_div_zero 0
		.amdhsa_exception_fp_ieee_overflow 0
		.amdhsa_exception_fp_ieee_underflow 0
		.amdhsa_exception_fp_ieee_inexact 0
		.amdhsa_exception_int_div_zero 0
	.end_amdhsa_kernel

; __global__ void __launch_bounds__(NTHR, 2) fwd_megakernel(Params p0) {
;   __shared__ __attribute__((aligned(16))) char lds[65536];
;   cg::grid_group grid = cg::this_grid();
;   __shared__ uint4 xb_words;
amdhsa.kernels:
  - .agpr_count:     0
    .args:
      - .offset:         0
        .size:           256
        .value_kind:     by_value
      - .offset:         256
        .size:           4
        .value_kind:     hidden_block_count_x
      - .offset:         260
        .size:           4
        .value_kind:     hidden_block_count_y
      - .offset:         264
        .size:           4
        .value_kind:     hidden_block_count_z
      - .offset:         268
        .size:           2
        .value_kind:     hidden_group_size_x
      - .offset:         270
        .size:           2
        .value_kind:     hidden_group_size_y
      - .offset:         272
        .size:           2
        .value_kind:     hidden_group_size_z
      - .offset:         274
        .size:           2
        .value_kind:     hidden_remainder_x
      - .offset:         276
        .size:           2
        .value_kind:     hidden_remainder_y
      - .offset:         278
        .size:           2
        .value_kind:     hidden_remainder_z
      - .offset:         296
        .size:           8
        .value_kind:     hidden_global_offset_x
      - .offset:         304
        .size:           8
        .value_kind:     hidden_global_offset_y
      - .offset:         312
        .size:           8
        .value_kind:     hidden_global_offset_z
      - .offset:         320
        .size:           2
        .value_kind:     hidden_grid_dims
      - .offset:         344
        .size:           8
        .value_kind:     hidden_multigrid_sync_arg
    .group_segment_fixed_size: 65552
    .kernarg_segment_align: 8
    .kernarg_segment_size: 512
    .language:       OpenCL C
    .language_version:
      - 2
      - 0
    .max_flat_workgroup_size: 256
    .name:           _Z14fwd_megakernel6Params
    .private_segment_fixed_size: 0
    .sgpr_count:     106
    .sgpr_spill_count: 192
    .symbol:         _Z14fwd_megakernel6Params.kd
    .uniform_work_group_size: 1
    .uses_dynamic_stack: false
    .vgpr_count:     256
    .vgpr_spill_count: 0
    .wavefront_size: 64
